# v22 plus attention QK/PV LDS fragment reads software-pipelined, gmlp epilogue gain loads hoisted, gmlp MFMA loop reads batched, gmlp V-transpose LDS image skewed against write bank conflicts
# speedup vs baseline: 1.0049x; 1.0049x over previous
; #define LAS __attribute__((address_space(3)))
; #define MFMA32(a, b, c) __builtin_amdgcn_mfma_f32_32x32x16_bf16((a), (b), (c), 0, 0, 0)
; __device__ __forceinline__ void attn_unit(LAS unsigned char* lds, const bf16* Q, const bf16* K, const bf16* KV, bf16* Y, const float* gout, int b, int h, int qb, const int tid) {
;     ...
; #pragma unroll
;             for (int dk = 0; dk < 12; ++dk) {
;                 const unsigned kb_ = (dk & 2) ? kb1 : kb0;
;                 const bf16x8 k0 = *(const LAS bf16x8*)(lds + bo + kb_ + dk * 32), k1 = *(const LAS bf16x8*)(lds + bo + kb_ + 32 * KP + dk * 32);
;                 s0 = MFMA32(k0, qf[dk], s0); s1 = MFMA32(k1, qf[dk], s1);
;             }
;             if (t >= 4 * qb) {
;                 const int kb0 = 64 * t + 8 * hi;
; #pragma unroll
;                 for (int r = 0; r < 16; ++r) { const int key = kb0 + 16 * (r >> 3) + (r & 7); if (key > qrow) s0[r] = -1e30f; if (key + 32 > qrow) s1[r] = -1e30f; }
;             }
.LBB0_34:
	global_load_dwordx4 v[10:13], v[208:209], off offset:-128
	global_load_dwordx4 v[164:167], v[208:209], off
	global_load_dwordx4 v[168:171], v[208:209], off offset:128
	s_bitcmp1_b32 s21, 0
	s_cselect_b32 s25, 0xb400, 0
	s_cmp_le_i32 s21, s19
	s_cselect_b64 s[4:5], -1, 0
	s_cmp_gt_i32 s21, s19
	s_cbranch_scc1 .LBB0_38
	v_add_u32_e32 v1, s25, v228
	v_add_u32_e32 v247, v1, v227
	ds_read_b128 v[2:5], v247
	v_add_u32_e32 v1, v1, v229
	s_cmp_lt_u32 s21, s17
	ds_read_b128 v[6:9], v247 offset:12800
	ds_read_b128 v[248:251], v247 offset:32
	s_waitcnt lgkmcnt(2)
	v_mfma_f32_32x32x16_bf16 v[96:111], v[2:5], v[160:163], 0
	ds_read_b128 v[2:5], v247 offset:12832
	s_waitcnt lgkmcnt(2)
	v_mfma_f32_32x32x16_bf16 v[80:95], v[6:9], v[160:163], 0
	ds_read_b128 v[6:9], v1 offset:64
	s_waitcnt lgkmcnt(2)
	v_mfma_f32_32x32x16_bf16 v[96:111], v[248:251], v[156:159], v[96:111]
	ds_read_b128 v[248:251], v1 offset:12864
	s_waitcnt lgkmcnt(2)
	v_mfma_f32_32x32x16_bf16 v[80:95], v[2:5], v[156:159], v[80:95]
	ds_read_b128 v[2:5], v1 offset:96
	s_waitcnt lgkmcnt(2)
	v_mfma_f32_32x32x16_bf16 v[96:111], v[6:9], v[152:155], v[96:111]
	ds_read_b128 v[6:9], v1 offset:12896
	s_waitcnt lgkmcnt(2)
	v_mfma_f32_32x32x16_bf16 v[80:95], v[248:251], v[152:155], v[80:95]
	ds_read_b128 v[248:251], v247 offset:128
	s_waitcnt lgkmcnt(2)
	v_mfma_f32_32x32x16_bf16 v[96:111], v[2:5], v[148:151], v[96:111]
	ds_read_b128 v[2:5], v247 offset:12928
	s_waitcnt lgkmcnt(2)
	v_mfma_f32_32x32x16_bf16 v[80:95], v[6:9], v[148:151], v[80:95]
	ds_read_b128 v[6:9], v247 offset:160
	s_waitcnt lgkmcnt(2)
	v_mfma_f32_32x32x16_bf16 v[96:111], v[248:251], v[144:147], v[96:111]
	ds_read_b128 v[248:251], v247 offset:12960
	s_waitcnt lgkmcnt(2)
	v_mfma_f32_32x32x16_bf16 v[80:95], v[2:5], v[144:147], v[80:95]
	ds_read_b128 v[2:5], v1 offset:192
	s_waitcnt lgkmcnt(2)
	v_mfma_f32_32x32x16_bf16 v[96:111], v[6:9], v[140:143], v[96:111]
	ds_read_b128 v[6:9], v1 offset:12992
	s_waitcnt lgkmcnt(2)
	v_mfma_f32_32x32x16_bf16 v[80:95], v[248:251], v[140:143], v[80:95]
	ds_read_b128 v[248:251], v1 offset:224
	s_waitcnt lgkmcnt(2)
	v_mfma_f32_32x32x16_bf16 v[96:111], v[2:5], v[136:139], v[96:111]
	ds_read_b128 v[2:5], v1 offset:13024
	s_waitcnt lgkmcnt(2)
	v_mfma_f32_32x32x16_bf16 v[80:95], v[6:9], v[136:139], v[80:95]
	ds_read_b128 v[6:9], v247 offset:256
	s_waitcnt lgkmcnt(2)
	v_mfma_f32_32x32x16_bf16 v[96:111], v[248:251], v[132:135], v[96:111]
	ds_read_b128 v[248:251], v247 offset:13056
	s_waitcnt lgkmcnt(2)
	v_mfma_f32_32x32x16_bf16 v[80:95], v[2:5], v[132:135], v[80:95]
	ds_read_b128 v[2:5], v247 offset:288
	s_waitcnt lgkmcnt(2)
	v_mfma_f32_32x32x16_bf16 v[96:111], v[6:9], v[128:131], v[96:111]
	ds_read_b128 v[6:9], v247 offset:13088
	s_waitcnt lgkmcnt(2)
	v_mfma_f32_32x32x16_bf16 v[80:95], v[248:251], v[128:131], v[80:95]
	ds_read_b128 v[248:251], v1 offset:320
	s_waitcnt lgkmcnt(2)
	v_mfma_f32_32x32x16_bf16 v[96:111], v[2:5], v[124:127], v[96:111]
	ds_read_b128 v[2:5], v1 offset:13120
	s_waitcnt lgkmcnt(2)
	v_mfma_f32_32x32x16_bf16 v[80:95], v[6:9], v[124:127], v[80:95]
	ds_read_b128 v[6:9], v1 offset:352
	s_waitcnt lgkmcnt(2)
	v_mfma_f32_32x32x16_bf16 v[96:111], v[248:251], v[120:123], v[96:111]
	ds_read_b128 v[248:251], v1 offset:13152
	s_waitcnt lgkmcnt(2)
	v_mfma_f32_32x32x16_bf16 v[80:95], v[2:5], v[120:123], v[80:95]
	s_waitcnt lgkmcnt(1)
	v_mfma_f32_32x32x16_bf16 v[96:111], v[6:9], v[116:119], v[96:111]
	s_waitcnt lgkmcnt(0)
	v_mfma_f32_32x32x16_bf16 v[80:95], v[248:251], v[116:119], v[80:95]
	s_cbranch_scc1 .LBB0_37
	v_subrev_u32_e32 v2, 23, v234
	v_subrev_u32_e32 v1, 55, v234
	v_cmp_le_i32_e32 vcc, v2, v206
	s_nop 7
	v_cndmask_b32_e32 v80, v220, v80, vcc
	v_cmp_lt_i32_e32 vcc, v1, v206
	s_nop 1
	v_cndmask_b32_e32 v97, v220, v97, vcc
	v_cmp_le_i32_e32 vcc, v1, v206
	v_subrev_u32_e32 v1, 22, v234
	s_nop 0
	v_cndmask_b32_e32 v96, v220, v96, vcc
	v_cmp_le_i32_e32 vcc, v1, v206
	v_subrev_u32_e32 v1, 53, v234
	s_nop 0
	v_cndmask_b32_e32 v81, v220, v81, vcc
	v_cmp_le_i32_e32 vcc, v1, v206
	v_subrev_u32_e32 v1, 21, v234
	s_nop 0
	v_cndmask_b32_e32 v98, v220, v98, vcc
	v_cmp_le_i32_e32 vcc, v1, v206
	v_subrev_u32_e32 v1, 52, v234
	s_nop 0
	v_cndmask_b32_e32 v82, v220, v82, vcc
	v_cmp_le_i32_e32 vcc, v1, v206
	v_subrev_u32_e32 v1, 20, v234
	s_nop 0
	v_cndmask_b32_e32 v99, v220, v99, vcc
	v_cmp_le_i32_e32 vcc, v1, v206
	v_subrev_u32_e32 v1, 51, v234
	s_nop 0
	v_cndmask_b32_e32 v83, v220, v83, vcc
	v_cmp_le_i32_e32 vcc, v1, v206
	v_subrev_u32_e32 v1, 19, v234
	s_nop 0
	v_cndmask_b32_e32 v100, v220, v100, vcc
	v_cmp_le_i32_e32 vcc, v1, v206
	v_subrev_u32_e32 v1, 50, v234
	s_nop 0
	v_cndmask_b32_e32 v84, v220, v84, vcc
	v_cmp_le_i32_e32 vcc, v1, v206
	v_subrev_u32_e32 v1, 18, v234
	s_nop 0
	v_cndmask_b32_e32 v101, v220, v101, vcc
	v_cmp_le_i32_e32 vcc, v1, v206
	v_subrev_u32_e32 v1, 49, v234
	s_nop 0
	v_cndmask_b32_e32 v85, v220, v85, vcc
	v_cmp_le_i32_e32 vcc, v1, v206
	v_subrev_u32_e32 v1, 17, v234
	s_nop 0
	v_cndmask_b32_e32 v102, v220, v102, vcc
	v_cmp_le_i32_e32 vcc, v1, v206
	v_subrev_u32_e32 v1, 48, v234
	s_nop 0
	v_cndmask_b32_e32 v86, v220, v86, vcc
	v_cmp_le_i32_e32 vcc, v1, v206
	v_add_u32_e32 v1, -16, v234
	s_nop 0
	v_cndmask_b32_e32 v103, v220, v103, vcc
	v_cmp_le_i32_e32 vcc, v1, v206
	v_subrev_u32_e32 v1, 39, v234
	s_nop 0
	v_cndmask_b32_e32 v87, v220, v87, vcc
	v_cmp_le_i32_e32 vcc, v1, v206
	v_add_u32_e32 v1, -7, v234
	s_nop 0
	v_cndmask_b32_e32 v104, v220, v104, vcc
	v_cmp_le_i32_e32 vcc, v1, v206
	v_subrev_u32_e32 v1, 38, v234
	s_nop 0
	v_cndmask_b32_e32 v88, v220, v88, vcc
	v_cmp_le_i32_e32 vcc, v1, v206
	v_add_u32_e32 v1, -6, v234
	s_nop 0
	v_cndmask_b32_e32 v105, v220, v105, vcc
	v_cmp_le_i32_e32 vcc, v1, v206
	v_subrev_u32_e32 v1, 37, v234
	s_nop 0
	v_cndmask_b32_e32 v89, v220, v89, vcc
	v_cmp_le_i32_e32 vcc, v1, v206
	v_add_u32_e32 v1, -5, v234
	s_nop 0
	v_cndmask_b32_e32 v106, v220, v106, vcc
	v_cmp_le_i32_e32 vcc, v1, v206
	v_subrev_u32_e32 v1, 36, v234
	s_nop 0
	v_cndmask_b32_e32 v90, v220, v90, vcc
	v_cmp_le_i32_e32 vcc, v1, v206
	v_add_u32_e32 v1, -4, v234
	s_nop 0
	v_cndmask_b32_e32 v107, v220, v107, vcc
	v_cmp_le_i32_e32 vcc, v1, v206
	v_subrev_u32_e32 v1, 35, v234
	s_nop 0
	v_cndmask_b32_e32 v91, v220, v91, vcc
	v_cmp_le_i32_e32 vcc, v1, v206
	v_add_u32_e32 v1, -3, v234
	s_nop 0
	v_cndmask_b32_e32 v108, v220, v108, vcc
	v_cmp_le_i32_e32 vcc, v1, v206
	v_subrev_u32_e32 v1, 34, v234
	s_nop 0
	v_cndmask_b32_e32 v92, v220, v92, vcc
	v_cmp_le_i32_e32 vcc, v1, v206
	v_add_u32_e32 v1, -2, v234
	s_nop 0
	v_cndmask_b32_e32 v109, v220, v109, vcc
	v_cmp_le_i32_e32 vcc, v1, v206
	v_subrev_u32_e32 v1, 33, v234
	s_nop 0
	v_cndmask_b32_e32 v93, v220, v93, vcc
	v_cmp_le_i32_e32 vcc, v1, v206
	v_add_u32_e32 v1, -1, v234
	s_nop 0
	v_cndmask_b32_e32 v110, v220, v110, vcc
	v_cmp_le_i32_e32 vcc, v1, v206
	v_subrev_u32_e32 v1, 32, v234
	s_nop 0
	v_cndmask_b32_e32 v94, v220, v94, vcc
	v_cmp_le_i32_e32 vcc, v1, v206
	s_nop 1
	v_cndmask_b32_e32 v111, v220, v111, vcc
	v_cmp_le_i32_e32 vcc, v234, v206
	s_nop 1
	v_cndmask_b32_e32 v95, v220, v95, vcc

; #define LAS __attribute__((address_space(3)))
; __device__ __forceinline__ v4i16_t vtr(LAS unsigned char* p) { return __builtin_amdgcn_ds_read_tr16_b64_v4i16((LAS v4i16_t*)p); }
; #define MFMA32(a, b, c) __builtin_amdgcn_mfma_f32_32x32x16_bf16((a), (b), (c), 0, 0, 0)
; __device__ __forceinline__ void attn_unit(LAS unsigned char* lds, const bf16* Q, const bf16* K, const bf16* KV, bf16* Y, const float* gout, int b, int h, int qb, const int tid) {
;     ...
;         if (more) {
; #pragma unroll
;             for (int i = 0; i < 3; ++i) *(LAS u32x4*)(lds + nb + kdst + i * 128) = kr[i];
; #pragma unroll
;             for (int i = 0; i < 2; ++i) vr[i] = *(const u32x4*)(vsrc + (size_t)(t + 1) * 64 * 2048 + i * 64);
;         }
;         if (active) {
; #pragma unroll
;             for (int kc = 0; kc < 4; ++kc) {
;                 const bf16x8 pf = __builtin_bit_cast(bf16x8, pw[kc]);
; #pragma unroll
;                 for (int d = 0; d < 4; ++d) { const v4i16_t vlo = vtr(lds + bo + voff + kc * 16 * VP + d * 64), vhi = vtr(lds + bo + voff + kc * 16 * VP + 4 * VP + d * 64);
;                     const bf16x8 vf = (bf16x8){vlo[0], vlo[1], vlo[2], vlo[3], vhi[0], vhi[1], vhi[2], vhi[3]}; o[d] = MFMA32(vf, pf, o[d]); }
;             }
.LBB0_38:
	s_add_i32 s21, s21, 1
	s_bitcmp1_b32 s21, 0
	s_cselect_b32 s27, 0xb400, 0
	v_add_u32_e32 v1, s27, v225
	s_waitcnt vmcnt(2)
	ds_write_b128 v1, v[10:13]
	s_waitcnt vmcnt(1)
	ds_write_b128 v1, v[164:167] offset:128
	s_waitcnt vmcnt(0)
	ds_write_b128 v1, v[168:171] offset:256
	global_load_dwordx4 v[10:13], v[210:211], off offset:-128
	global_load_dwordx4 v[88:91], v[210:211], off
	s_andn2_b64 vcc, exec, s[4:5]
	s_cbranch_vccnz .LBB0_33
	v_add_u32_e32 v1, s25, v231
	ds_read_b64_tr_b16 v[92:93], v1 offset:25600
	ds_read_b64_tr_b16 v[94:95], v1 offset:26880
	ds_read_b64_tr_b16 v[96:97], v1 offset:25664
	ds_read_b64_tr_b16 v[98:99], v1 offset:26944
	ds_read_b64_tr_b16 v[100:101], v1 offset:25728
	ds_read_b64_tr_b16 v[102:103], v1 offset:27008
	ds_read_b64_tr_b16 v[104:105], v1 offset:25792
	ds_read_b64_tr_b16 v[106:107], v1 offset:27072
	ds_read_b64_tr_b16 v[108:109], v1 offset:30720
	ds_read_b64_tr_b16 v[110:111], v1 offset:32000
	s_waitcnt lgkmcnt(8)
	v_mfma_f32_32x32x16_bf16 v[64:79], v[92:95], v[84:87], v[64:79]
	ds_read_b64_tr_b16 v[92:93], v1 offset:30784
	ds_read_b64_tr_b16 v[94:95], v1 offset:32064
	s_waitcnt lgkmcnt(8)
	v_mfma_f32_32x32x16_bf16 v[48:63], v[96:99], v[84:87], v[48:63]
	ds_read_b64_tr_b16 v[96:97], v1 offset:30848
	ds_read_b64_tr_b16 v[98:99], v1 offset:32128
	s_waitcnt lgkmcnt(8)
	v_mfma_f32_32x32x16_bf16 v[32:47], v[100:103], v[84:87], v[32:47]
	ds_read_b64_tr_b16 v[100:101], v1 offset:30912
	ds_read_b64_tr_b16 v[102:103], v1 offset:32192
	s_waitcnt lgkmcnt(8)
	v_mfma_f32_32x32x16_bf16 v[16:31], v[104:107], v[84:87], v[16:31]
	ds_read_b64_tr_b16 v[104:105], v1 offset:35840
	ds_read_b64_tr_b16 v[106:107], v1 offset:37120
	s_waitcnt lgkmcnt(8)
	v_mfma_f32_32x32x16_bf16 v[64:79], v[108:111], v[80:83], v[64:79]
	ds_read_b64_tr_b16 v[108:109], v1 offset:35904
	ds_read_b64_tr_b16 v[110:111], v1 offset:37184
	s_waitcnt lgkmcnt(8)
	v_mfma_f32_32x32x16_bf16 v[48:63], v[92:95], v[80:83], v[48:63]
	ds_read_b64_tr_b16 v[92:93], v1 offset:35968
	ds_read_b64_tr_b16 v[94:95], v1 offset:37248
	s_waitcnt lgkmcnt(8)
	v_mfma_f32_32x32x16_bf16 v[32:47], v[96:99], v[80:83], v[32:47]
	ds_read_b64_tr_b16 v[96:97], v1 offset:36032
	ds_read_b64_tr_b16 v[98:99], v1 offset:37312
	s_waitcnt lgkmcnt(8)
	v_mfma_f32_32x32x16_bf16 v[16:31], v[100:103], v[80:83], v[16:31]
	ds_read_b64_tr_b16 v[100:101], v1 offset:40960
	ds_read_b64_tr_b16 v[102:103], v1 offset:42240
	s_waitcnt lgkmcnt(8)
	v_mfma_f32_32x32x16_bf16 v[64:79], v[104:107], v[6:9], v[64:79]
	ds_read_b64_tr_b16 v[104:105], v1 offset:41024
	ds_read_b64_tr_b16 v[106:107], v1 offset:42304
	s_waitcnt lgkmcnt(8)
	v_mfma_f32_32x32x16_bf16 v[48:63], v[108:111], v[6:9], v[48:63]
	ds_read_b64_tr_b16 v[108:109], v1 offset:41088
	ds_read_b64_tr_b16 v[110:111], v1 offset:42368
	s_waitcnt lgkmcnt(8)
	v_mfma_f32_32x32x16_bf16 v[32:47], v[92:95], v[6:9], v[32:47]
	ds_read_b64_tr_b16 v[92:93], v1 offset:41152
	ds_read_b64_tr_b16 v[94:95], v1 offset:42432
	s_waitcnt lgkmcnt(8)
	v_mfma_f32_32x32x16_bf16 v[16:31], v[96:99], v[6:9], v[16:31]
	s_waitcnt lgkmcnt(6)
	v_mfma_f32_32x32x16_bf16 v[64:79], v[100:103], v[2:5], v[64:79]
	s_waitcnt lgkmcnt(4)
	v_mfma_f32_32x32x16_bf16 v[48:63], v[104:107], v[2:5], v[48:63]
	s_waitcnt lgkmcnt(2)
	v_mfma_f32_32x32x16_bf16 v[32:47], v[108:111], v[2:5], v[32:47]
	s_waitcnt lgkmcnt(0)
	v_mfma_f32_32x32x16_bf16 v[16:31], v[92:95], v[2:5], v[16:31]
	s_branch .LBB0_33

; __device__ __forceinline__ unsigned cvt_pk_bf16(float lo, float hi) { f32x2 v = {lo, hi}; bf16x2_t b = __builtin_convertvector(v, bf16x2_t); return __builtin_bit_cast(unsigned, b); }
; #define LAS __attribute__((address_space(3)))
; __device__ __forceinline__ void gmlp_phase(LAS unsigned char* lds, const bf16* Z, const float* w_s, const float* b_s, const float* gout, const float* ssv, const float* gv, bf16* Y, int vcu, int G, const int tid) {
;     const int lane = tid & 63, l16 = lane & 15, q4 = lane >> 4; const int wid = __builtin_amdgcn_readfirstlane(tid >> 6);
;     int gcur = -1;
;     u32x4 vreg[4]; float rvreg[4];
;     if (vcu < 2048) { const int g = vcu & 7; const size_t tok0 = (size_t)(vcu >> 3) * 128;
; #pragma unroll
;         for (int i = 0; i < 4; ++i) { const int p = tid + 512 * i, s = p >> 4, seg = p & 15; vreg[i] = *(const u32x4*)(Z + (tok0 + s) * ZLD + 1024 + g * 128 + seg * 8); rvreg[i] = ssv[tok0 + s]; } }
;     for (int un = vcu; un < 2048; un += G) {
;         const int g = un & 7, bc = un >> 3;
;         const size_t tok0 = (size_t)bc * 128;
;         __syncthreads();
;         if (g != gcur) {
;             gcur = g;
; #pragma unroll
;             for (int i = 0; i < 8; ++i) { const int p = tid + 512 * i, t = p >> 5, s = (p & 31) * 4; const f32x4 w = *(const f32x4*)(w_s + (size_t)g * 16384 + t * 128 + s);
;                 u32x2 o; o.x = cvt_pk_bf16(s <= t ? w.x : 0.f, s + 1 <= t ? w.y : 0.f); o.y = cvt_pk_bf16(s + 2 <= t ? w.z : 0.f, s + 3 <= t ? w.w : 0.f);
;                 *(LAS u32x2*)(lds + t * WP + s * 2) = o; }
;         }
; #pragma unroll
;         for (int i = 0; i < 4; ++i) { const int p = tid + 512 * i, s = p >> 4, seg = p & 15; const u32x4 v = vreg[i];
;             const float rv = __builtin_amdgcn_rsqf(rvreg[i] * (1.0f / 1024.0f) + EPS); const f32x4 g0 = *(const f32x4*)(gv + g * 128 + seg * 8), g1 = *(const f32x4*)(gv + g * 128 + seg * 8 + 4);
;             LAS unsigned short* dst = (LAS unsigned short*)(lds + WBYTES + (seg * 8) * WP + s * 2);
.LBB0_457:
	v_readlane_b32 s4, v252, 26
	v_readlane_b32 s5, v252, 27
	s_andn2_b64 vcc, exec, s[4:5]
	s_cbranch_vccnz .LBB0_469
	v_readlane_b32 s4, v253, 16
	v_readlane_b32 s5, v253, 17
	s_andn2_b64 vcc, exec, s[4:5]
	v_readfirstlane_b32 s0, v223
	s_cbranch_vccnz .LBB0_469
	v_ashrrev_i32_e32 v50, 4, v223
	v_readlane_b32 s14, v253, 18
	v_lshlrev_b32_e32 v2, 3, v223
	v_ashrrev_i32_e32 v51, 31, v50
	v_readlane_b32 s15, v253, 19
	v_and_b32_e32 v18, 0x78, v2
	v_mov_b64_e32 v[14:15], s[98:99]
	s_waitcnt lgkmcnt(0)
	v_lshl_add_u64 v[2:3], s[14:15], 0, v[50:51]
	s_movk_i32 s3, 0x1a00
	v_readlane_b32 s16, v254, 44
	v_mad_u64_u32 v[4:5], s[12:13], v2, s3, v[14:15]
	v_readlane_b32 s17, v254, 45
	v_mad_i32_i24 v5, v3, s3, v5
	s_mov_b32 s17, s1
	v_readlane_b32 s22, v252, 44
	v_add_u32_e32 v19, 0x200, v223
	v_lshl_add_u64 v[4:5], v[4:5], 0, s[16:17]
	v_lshlrev_b32_e32 v16, 1, v18
	v_mov_b32_e32 v17, v0
	v_readlane_b32 s23, v252, 45
	v_ashrrev_i32_e32 v52, 4, v19
	v_lshl_add_u64 v[4:5], v[4:5], 0, v[16:17]
	v_lshl_add_u64 v[6:7], v[2:3], 2, s[22:23]
	v_ashrrev_i32_e32 v53, 31, v52
	s_load_dwordx4 s[4:7], s[90:91], 0x40
	s_load_dwordx2 s[10:11], s[90:91], 0x88
	global_load_dwordx4 v[2:5], v[4:5], off offset:2048
	s_nop 0
	global_load_dword v87, v[6:7], off
	v_lshl_add_u64 v[6:7], s[14:15], 0, v[52:53]
	v_mad_u64_u32 v[8:9], s[12:13], v6, s3, v[14:15]
	v_mad_i32_i24 v9, v7, s3, v9
	v_add_u32_e32 v22, 0x400, v223
	v_lshl_add_u64 v[8:9], v[8:9], 0, s[16:17]
	v_ashrrev_i32_e32 v54, 4, v22
	v_lshl_add_u64 v[8:9], v[8:9], 0, v[16:17]
	v_lshl_add_u64 v[10:11], v[6:7], 2, s[22:23]
	v_ashrrev_i32_e32 v55, 31, v54
	global_load_dwordx4 v[6:9], v[8:9], off offset:2048
	s_nop 0
	global_load_dword v106, v[10:11], off
	v_lshl_add_u64 v[10:11], s[14:15], 0, v[54:55]
	v_mad_u64_u32 v[12:13], s[12:13], v10, s3, v[14:15]
	v_mad_i32_i24 v13, v11, s3, v13
	v_add_u32_e32 v23, 0x600, v223
	v_lshl_add_u64 v[12:13], v[12:13], 0, s[16:17]
	v_ashrrev_i32_e32 v56, 4, v23
	v_lshl_add_u64 v[12:13], v[12:13], 0, v[16:17]
	v_lshl_add_u64 v[20:21], v[10:11], 2, s[22:23]
	v_ashrrev_i32_e32 v57, 31, v56
	global_load_dwordx4 v[10:13], v[12:13], off offset:2048
	s_nop 0
	global_load_dword v107, v[20:21], off
	v_lshl_add_u64 v[20:21], s[14:15], 0, v[56:57]
	v_mad_u64_u32 v[14:15], s[12:13], v20, s3, v[14:15]
	v_mad_i32_i24 v15, v21, s3, v15
	v_lshl_add_u64 v[14:15], v[14:15], 0, s[16:17]
	v_lshl_add_u64 v[14:15], v[14:15], 0, v[16:17]
	v_lshl_add_u64 v[20:21], v[20:21], 2, s[22:23]
	global_load_dwordx4 v[14:17], v[14:15], off offset:2048
	s_nop 0
	global_load_dword v83, v[20:21], off
	v_xor_b32_e32 v28, 16, v217
	v_cmp_lt_i32_e32 vcc, v28, v219
	s_mov_b32 s12, s16
	v_writelane_b32 v254, s12, 44
	v_cndmask_b32_e32 v28, v217, v28, vcc
	v_cmp_lt_i32_e32 vcc, v218, v219
	v_and_b32_e32 v24, 0x7c, v176
	v_lshlrev_b32_e32 v108, 2, v28
	v_cndmask_b32_e32 v28, v217, v218, vcc
	v_add_u32_e32 v32, 0x800, v223
	v_add_u32_e32 v33, 0xa00, v223
	v_add_u32_e32 v34, 0xc00, v223
	v_add_u32_e32 v35, 0xe00, v223
	v_writelane_b32 v254, s13, 45
	v_lshlrev_b32_e32 v20, 2, v24
	v_mov_b32_e32 v21, v0
	v_or_b32_e32 v26, 3, v24
	s_movk_i32 s15, 0x110
	s_ashr_i32 s14, s0, 2
	s_ashr_i32 s3, s0, 7
	v_lshlrev_b32_e32 v109, 2, v28
	v_ashrrev_i32_e32 v28, 5, v223
	v_ashrrev_i32_e32 v29, 5, v19
	v_ashrrev_i32_e32 v30, 5, v22
	v_ashrrev_i32_e32 v31, 5, v23
	v_ashrrev_i32_e32 v32, 5, v32
	v_ashrrev_i32_e32 v33, 5, v33
	v_ashrrev_i32_e32 v34, 5, v34
	v_ashrrev_i32_e32 v35, 5, v35
	s_waitcnt lgkmcnt(0)
	v_lshl_add_u64 v[58:59], s[6:7], 0, v[20:21]
	s_cmp_gt_i32 s3, -1
	v_cmp_gt_i32_e64 s[46:47], v26, v28
	v_cmp_gt_i32_e64 s[54:55], v26, v29
	v_cmp_gt_i32_e64 s[62:63], v26, v30
	v_cmp_gt_i32_e64 s[70:71], v26, v31
	v_cmp_gt_i32_e64 s[78:79], v26, v32
	v_cmp_gt_i32_e64 s[86:87], v26, v33
	v_cmp_gt_i32_e64 s[94:95], v26, v34
	v_cmp_gt_i32_e64 s[6:7], v26, v35
	v_mad_u32_u24 v26, v1, s15, v110
	v_readlane_b32 s0, v254, 46
	v_or_b32_e32 v25, 2, v24
	v_lshlrev_b32_e32 v20, 2, v18
	v_and_or_b32 v62, s14, -16, v1
	s_cselect_b64 s[12:13], -1, 0
	v_add_u32_e32 v1, s0, v26
	s_lshr_b32 s0, s14, 4
	v_lshl_add_u64 v[60:61], s[4:5], 0, v[20:21]
	v_cmp_gt_i32_e64 s[44:45], v25, v28
	v_cmp_gt_i32_e64 s[52:53], v25, v29
	v_cmp_gt_i32_e64 s[60:61], v25, v30
	v_cmp_gt_i32_e64 s[68:69], v25, v31
	v_cmp_gt_i32_e64 s[76:77], v25, v32
	v_cmp_gt_i32_e64 s[84:85], v25, v33
	v_cmp_gt_i32_e64 s[92:93], v25, v34
	v_cmp_gt_i32_e64 s[4:5], v25, v35
	v_ashrrev_i32_e32 v25, 3, v223
	v_ashrrev_i32_e32 v19, 3, v19
	v_ashrrev_i32_e32 v22, 3, v22
	v_ashrrev_i32_e32 v23, 3, v23
	s_mulk_i32 s0, 0x1100
	v_lshl_add_u32 v27, v24, 1, 0
	v_mad_u32_u24 v21, v18, s15, 0
	v_lshlrev_b32_e32 v20, 2, v111
	v_mov_b32_e32 v111, v0
	v_lshlrev_b32_e32 v66, 7, v28
	v_cmp_gt_i32_e64 s[40:41], v24, v28
	v_cmp_lt_i32_e64 s[42:43], v24, v28
	v_mul_lo_u32 v28, v28, s15
	v_lshlrev_b32_e32 v68, 7, v29
	v_cmp_gt_i32_e64 s[48:49], v24, v29
	v_cmp_lt_i32_e64 s[50:51], v24, v29
	v_mul_lo_u32 v29, v29, s15
	v_lshlrev_b32_e32 v70, 7, v30
	v_cmp_gt_i32_e64 s[56:57], v24, v30
	v_cmp_lt_i32_e64 s[58:59], v24, v30
	v_mul_lo_u32 v30, v30, s15
	v_lshlrev_b32_e32 v72, 7, v31
	v_cmp_gt_i32_e64 s[64:65], v24, v31
	v_cmp_lt_i32_e64 s[66:67], v24, v31
	v_mul_lo_u32 v31, v31, s15
	v_lshlrev_b32_e32 v74, 7, v32
	v_cmp_gt_i32_e64 s[72:73], v24, v32
	v_cmp_lt_i32_e64 s[74:75], v24, v32
	v_mul_lo_u32 v32, v32, s15
	v_lshlrev_b32_e32 v76, 7, v33
	v_cmp_gt_i32_e64 s[80:81], v24, v33
	v_cmp_lt_i32_e64 s[82:83], v24, v33
	v_mul_lo_u32 v33, v33, s15
	v_lshlrev_b32_e32 v78, 7, v34
	v_cmp_gt_i32_e64 s[88:89], v24, v34
	v_cmp_lt_i32_e64 s[90:91], v24, v34
	v_mul_lo_u32 v34, v34, s15
	v_lshlrev_b32_e32 v80, 7, v35
	v_cmp_gt_i32_e64 s[96:97], v24, v35
	v_cmp_lt_i32_e64 s[98:99], v24, v35
	v_mul_lo_u32 v24, v35, s15
	v_and_b32_e32 v25, -2, v25
	v_and_b32_e32 v19, -2, v19
	v_and_b32_e32 v22, -2, v22
	v_and_b32_e32 v23, -2, v23
	s_add_i32 s0, s0, 0
	v_ashrrev_i32_e32 v63, 31, v62
	s_mov_b32 s9, -1
	v_lshl_add_u64 v[64:65], s[10:11], 0, v[110:111]
	v_ashrrev_i32_e32 v67, 31, v66
	v_ashrrev_i32_e32 v69, 31, v68
	v_ashrrev_i32_e32 v71, 31, v70
	v_ashrrev_i32_e32 v73, 31, v72
	v_ashrrev_i32_e32 v75, 31, v74
	v_ashrrev_i32_e32 v77, 31, v76
	v_ashrrev_i32_e32 v79, 31, v78
	v_ashrrev_i32_e32 v81, 31, v80
	s_add_i32 s3, s3, 1
	v_add_u32_e32 v110, s0, v26
	v_add_u32_e32 v111, v27, v28
	v_add_u32_e32 v116, v27, v29
	v_add_u32_e32 v117, v27, v30
	v_add_u32_e32 v118, v27, v31
	v_add_u32_e32 v119, v27, v32
	v_add_u32_e32 v120, v27, v33
	v_add_u32_e32 v121, v27, v34
	v_add_u32_e32 v122, v27, v24
	v_add_u32_e32 v123, v21, v25
	v_add_u32_e32 v124, v21, v19
	v_add_u32_e32 v125, v21, v22
	v_add_u32_e32 v126, v21, v23
	v_and_b32_e32 v186, 14, v212
	v_lshlrev_b32_e32 v186, 3, v186
	v_add_u32_e32 v123, v123, v186
	v_add_u32_e32 v124, v124, v186
	v_add_u32_e32 v125, v125, v186
	v_add_u32_e32 v126, v126, v186
	v_lshlrev_b32_e32 v82, 1, v18
	v_lshlrev_b32_e32 v84, 1, v20
	v_readlane_b32 s10, v253, 10
	s_waitcnt vmcnt(0)
	s_branch .LBB0_461
; __device__ __forceinline__ float bf_lo(unsigned u) { return __uint_as_float(u << 16); }
; __device__ __forceinline__ float bf_hi(unsigned u) { return __uint_as_float(u & 0xffff0000u); }
; __device__ __forceinline__ void gmlp_phase(LAS unsigned char* lds, const bf16* Z, const float* w_s, const float* b_s, const float* gout, const float* ssv, const float* gv, bf16* Y, int vcu, int G, const int tid) {
;     ...
;         const int t = tt;
;         float ss = 0.f;
; #pragma unroll
;         for (int d = 0; d < 8; ++d) { const u32x2 uu = ureg[d];
;             acc[d][0] = bf_lo(uu.x) * (acc[d][0] + bs); acc[d][1] = bf_hi(uu.x) * (acc[d][1] + bs); acc[d][2] = bf_lo(uu.y) * (acc[d][2] + bs); acc[d][3] = bf_hi(uu.y) * (acc[d][3] + bs);
;             ss += (acc[d][0] * acc[d][0] + acc[d][1] * acc[d][1]) + (acc[d][2] * acc[d][2] + acc[d][3] * acc[d][3]); }
;         ss += __shfl_xor(ss, 16); ss += __shfl_xor(ss, 32);
;         const float rn = 1.0f / sqrtf(ss * (1.0f / 128.0f) + EPS);
;         bf16* yp = Y + (tok0 + t) * DM + g * 128 + 4 * q4; const float* gp = gout + g * 128 + 4 * q4;
.LBB0_460:
	v_readlane_b32 s16, v252, 11
	s_waitcnt vmcnt(8)
	s_nop 3
	v_add_f32_e32 v140, v86, v18
	v_add_f32_e32 v144, v86, v19
	v_lshlrev_b64 v[18:19], 12, v[98:99]
	v_readlane_b32 s17, v252, 12
	v_mov_b32_e32 v139, v44
	v_mov_b32_e32 v44, v43
	v_lshl_add_u64 v[18:19], s[16:17], 0, v[18:19]
	v_add_f32_e32 v132, v86, v26
	v_add_f32_e32 v136, v86, v27
	s_waitcnt vmcnt(3)
	v_lshlrev_b32_e32 v27, 16, v103
	v_lshlrev_b32_e32 v26, 16, v102
	v_mov_b32_e32 v138, v42
	v_and_b32_e32 v103, 0xffff0000, v103
	v_and_b32_e32 v102, 0xffff0000, v102
	v_pk_add_f32 v[42:43], v[86:87], v[44:45] op_sel_hi:[0,1]
	v_lshl_add_u64 v[146:147], v[18:19], 0, s[0:1]
	s_lshl_b32 s0, s11, 2
	v_pk_mul_f32 v[42:43], v[42:43], v[102:103]
	s_waitcnt vmcnt(2)
	v_lshlrev_b32_e32 v102, 16, v100
	v_and_b32_e32 v103, 0xffff0000, v100
	v_lshlrev_b32_e32 v100, 16, v101
	v_and_b32_e32 v101, 0xffff0000, v101
	v_pk_add_f32 v[40:41], v[86:87], v[40:41] op_sel_hi:[0,1]
	v_lshl_add_u64 v[18:19], v[64:65], 0, s[0:1]
	v_pk_mul_f32 v[40:41], v[40:41], v[100:101]
	global_load_dwordx4 v[98:101], v[18:19], off
	global_load_dwordx4 v[224:227], v[18:19], off offset:64
	global_load_dwordx4 v[228:231], v[18:19], off offset:128
	global_load_dwordx4 v[232:235], v[18:19], off offset:192
	global_load_dwordx4 v[236:239], v[18:19], off offset:256
	global_load_dwordx4 v[240:243], v[18:19], off offset:320
	global_load_dwordx4 v[244:247], v[18:19], off offset:384
	global_load_dwordx4 v[248:251], v[18:19], off offset:448
	v_lshlrev_b32_e32 v150, 16, v96
	v_and_b32_e32 v151, 0xffff0000, v96
	v_pk_add_f32 v[34:35], v[86:87], v[34:35] op_sel_hi:[0,1]
	v_pk_mul_f32 v[34:35], v[34:35], v[150:151]
	v_lshlrev_b32_e32 v150, 16, v95
	v_and_b32_e32 v151, 0xffff0000, v95
	v_pk_add_f32 v[32:33], v[86:87], v[32:33] op_sel_hi:[0,1]
	v_pk_mul_f32 v[32:33], v[32:33], v[150:151]
	v_and_b32_e32 v134, 0xffff0000, v92
	v_mov_b32_e32 v137, v32
	v_mov_b32_e32 v135, v32
	v_pk_mul_f32 v[150:151], v[136:137], v[134:135]
	v_mov_b32_e32 v137, v33
	v_mov_b32_e32 v135, v33
	v_pk_mul_f32 v[152:153], v[136:137], v[134:135]
	v_lshlrev_b32_e32 v128, 16, v104
	v_and_b32_e32 v129, 0xffff0000, v104
	v_pk_add_f32 v[46:47], v[86:87], v[46:47] op_sel_hi:[0,1]
	v_pk_add_f32 v[38:39], v[86:87], v[38:39] op_sel_hi:[0,1]
	v_pk_mul_f32 v[152:153], v[150:151], v[152:153]
	v_pk_fma_f32 v[134:135], v[136:137], v[134:135], v[150:151]
	v_pk_mul_f32 v[46:47], v[46:47], v[128:129]
	v_pk_mul_f32 v[38:39], v[38:39], v[102:103]
	v_mov_b32_e32 v153, v135
	v_lshlrev_b32_e32 v134, 16, v94
	v_and_b32_e32 v135, 0xffff0000, v94
	v_pk_add_f32 v[30:31], v[86:87], v[30:31] op_sel_hi:[0,1]
	v_mul_f32_e32 v104, v46, v46
	v_lshlrev_b32_e32 v130, 16, v92
	v_mul_f32_e32 v92, v38, v38
	v_lshlrev_b32_e32 v148, 16, v97
	v_and_b32_e32 v149, 0xffff0000, v97
	v_pk_add_f32 v[36:37], v[86:87], v[36:37] op_sel_hi:[0,1]
	v_pk_mul_f32 v[30:31], v[30:31], v[134:135]
	v_pk_fma_f32 v[128:129], v[46:47], v[46:47], v[104:105] op_sel_hi:[1,1,0]
	v_lshlrev_b32_e32 v104, 16, v105
	v_and_b32_e32 v105, 0xffff0000, v105
	v_pk_add_f32 v[48:49], v[86:87], v[48:49] op_sel_hi:[0,1]
	v_pk_add_f32 v[138:139], v[86:87], v[138:139] op_sel_hi:[0,1]
	v_pk_fma_f32 v[102:103], v[38:39], v[38:39], v[92:93] op_sel_hi:[1,1,0]
	v_mul_f32_e32 v92, v40, v40
	v_pk_mul_f32 v[36:37], v[36:37], v[148:149]
	v_mov_b32_e32 v133, v30
	v_mov_b32_e32 v131, v30
	v_pk_mul_f32 v[48:49], v[48:49], v[104:105]
	v_pk_mul_f32 v[26:27], v[138:139], v[26:27]
	v_pk_fma_f32 v[138:139], v[40:41], v[40:41], v[92:93] op_sel_hi:[1,1,0]
	s_waitcnt vmcnt(8)
	v_lshlrev_b32_e32 v92, 16, v88
	v_and_b32_e32 v142, 0xffff0000, v88
	v_mul_f32_e32 v88, v36, v36
	v_pk_mul_f32 v[94:95], v[132:133], v[130:131]
	v_mov_b32_e32 v133, v31
	v_mov_b32_e32 v131, v31
	v_mul_f32_e32 v104, v48, v48
	v_pk_fma_f32 v[148:149], v[36:37], v[36:37], v[88:89] op_sel_hi:[1,1,0]
	v_mul_f32_e32 v88, v34, v34
	v_pk_mul_f32 v[134:135], v[132:133], v[130:131]
	v_pk_fma_f32 v[130:131], v[132:133], v[130:131], v[94:95]
	v_lshlrev_b32_e32 v132, 16, v93
	v_and_b32_e32 v133, 0xffff0000, v93
	v_pk_add_f32 v[28:29], v[86:87], v[28:29] op_sel_hi:[0,1]
	v_pk_fma_f32 v[104:105], v[48:49], v[48:49], v[104:105] op_sel_hi:[1,1,0]
	v_pk_fma_f32 v[96:97], v[34:35], v[34:35], v[88:89] op_sel_hi:[1,1,0]
	v_pk_mul_f32 v[28:29], v[28:29], v[132:133]
	v_pk_add_f32 v[104:105], v[128:129], v[104:105]
	v_pk_mul_f32 v[132:133], v[28:29], v[28:29]
	v_pk_add_f32 v[96:97], v[96:97], v[148:149]
	v_mov_b32_e32 v104, v133
	v_mov_b32_e32 v133, v97
	v_pk_add_f32 v[96:97], v[132:133], v[104:105]
	v_lshlrev_b32_e32 v104, 16, v91
	v_and_b32_e32 v105, 0xffff0000, v91
	v_pk_add_f32 v[24:25], v[86:87], v[24:25] op_sel_hi:[0,1]
	v_pk_mul_f32 v[24:25], v[24:25], v[104:105]
	v_pk_mul_f32 v[134:135], v[94:95], v[134:135]
	v_mov_b32_e32 v145, v24
	v_mov_b32_e32 v143, v24
	v_mov_b32_e32 v135, v131
	v_pk_mul_f32 v[104:105], v[144:145], v[142:143]
	v_mov_b32_e32 v145, v25
	v_mov_b32_e32 v143, v25
	v_pk_add_f32 v[130:131], v[134:135], v[152:153]
	v_pk_mul_f32 v[128:129], v[144:145], v[142:143]
	v_pk_add_f32 v[96:97], v[130:131], v[96:97]
	v_pk_mul_f32 v[128:129], v[104:105], v[128:129]
	v_pk_fma_f32 v[130:131], v[144:145], v[142:143], v[104:105]
	v_pk_add_f32 v[22:23], v[86:87], v[22:23] op_sel_hi:[0,1]
	v_mov_b32_e32 v129, v131
	v_lshlrev_b32_e32 v130, 16, v90
	v_and_b32_e32 v131, 0xffff0000, v90
	v_pk_mul_f32 v[90:91], v[22:23], v[130:131]
	v_pk_mul_f32 v[44:45], v[42:43], v[42:43]
	v_mov_b32_e32 v141, v90
	v_mov_b32_e32 v93, v90
	v_pk_mul_f32 v[130:131], v[140:141], v[92:93]
	v_mov_b32_e32 v141, v91
	v_mov_b32_e32 v93, v91
	v_pk_fma_f32 v[44:45], v[26:27], v[26:27], v[44:45]
	v_pk_mul_f32 v[22:23], v[140:141], v[92:93]
	v_lshlrev_b32_e32 v88, 16, v89
	v_and_b32_e32 v89, 0xffff0000, v89
	v_pk_add_f32 v[20:21], v[86:87], v[20:21] op_sel_hi:[0,1]
	v_pk_add_f32 v[44:45], v[44:45], v[44:45] op_sel_hi:[0,1]
	v_pk_add_f32 v[96:97], v[96:97], v[96:97] op_sel_hi:[0,1]
	v_pk_mul_f32 v[22:23], v[130:131], v[22:23]
	v_pk_fma_f32 v[92:93], v[140:141], v[92:93], v[130:131]
	v_pk_mul_f32 v[88:89], v[20:21], v[88:89]
	v_mov_b32_e32 v23, v93
	v_pk_mul_f32 v[20:21], v[88:89], v[88:89]
	v_pk_add_f32 v[92:93], v[102:103], v[138:139]
	v_pk_add_f32 v[44:45], v[44:45], v[96:97]
	v_mov_b32_e32 v92, v20
	v_mov_b32_e32 v44, v21
	v_pk_add_f32 v[22:23], v[22:23], v[128:129]
	v_pk_add_f32 v[20:21], v[92:93], v[44:45]
	v_mov_b32_e32 v85, v0
	v_pk_add_f32 v[20:21], v[22:23], v[20:21]
	v_lshl_add_u64 v[44:45], v[146:147], 0, v[84:85]
	v_add_f32_e32 v20, v20, v21
	ds_bpermute_b32 v21, v108, v20
	v_mov_b32_e32 v95, v150
	v_mov_b32_e32 v131, v104
	s_waitcnt lgkmcnt(0)
; __device__ __forceinline__ unsigned cvt_pk_bf16(float lo, float hi) { f32x2 v = {lo, hi}; bf16x2_t b = __builtin_convertvector(v, bf16x2_t); return __builtin_bit_cast(unsigned, b); }
; __device__ __forceinline__ void gmlp_phase(LAS unsigned char* lds, const bf16* Z, const float* w_s, const float* b_s, const float* gout, const float* ssv, const float* gv, bf16* Y, int vcu, int G, const int tid) {
;     ...
;         ss += __shfl_xor(ss, 16); ss += __shfl_xor(ss, 32);
;         const float rn = 1.0f / sqrtf(ss * (1.0f / 128.0f) + EPS);
;         bf16* yp = Y + (tok0 + t) * DM + g * 128 + 4 * q4; const float* gp = gout + g * 128 + 4 * q4;
; #pragma unroll
;         for (int d = 0; d < 8; ++d) { const f32x4 gg = *(const f32x4*)(gp + 16 * d); u32x2 w; w.x = cvt_pk_bf16(acc[d][0] * rn * gg.x, acc[d][1] * rn * gg.y); w.y = cvt_pk_bf16(acc[d][2] * rn * gg.z, acc[d][3] * rn * gg.w);
;             *(u32x2*)(yp + 16 * d) = w; }
	v_add_f32_e32 v20, v20, v21
	ds_bpermute_b32 v21, v109, v20
	s_waitcnt lgkmcnt(0)
	v_add_f32_e32 v20, v20, v21
	v_fmamk_f32 v20, v20, 0x3c000000, v214
	v_mul_f32_e32 v21, 0x4f800000, v20
	v_cmp_gt_f32_e64 s[10:11], s33, v20
	s_nop 1
	v_cndmask_b32_e64 v20, v20, v21, s[10:11]
	v_sqrt_f32_e32 v21, v20
	s_nop 0
	v_add_u32_e32 v22, -1, v21
	v_fma_f32 v23, -v22, v21, v20
	v_cmp_ge_f32_e32 vcc, 0, v23
	v_add_u32_e32 v23, 1, v21
	s_nop 0
	v_cndmask_b32_e32 v22, v21, v22, vcc
	v_fma_f32 v21, -v23, v21, v20
	v_cmp_lt_f32_e32 vcc, 0, v21
	s_nop 1
	v_cndmask_b32_e32 v21, v22, v23, vcc
	v_mul_f32_e32 v22, 0x37800000, v21
	v_cndmask_b32_e64 v21, v21, v22, s[10:11]
	v_cmp_class_f32_e32 vcc, v20, v215
	s_nop 1
	v_cndmask_b32_e32 v20, v21, v20, vcc
	v_div_scale_f32 v21, s[10:11], v20, v20, 1.0
	v_rcp_f32_e32 v22, v21
	s_mov_b32 s10, s14
	v_fma_f32 v23, -v21, v22, 1.0
	v_fmac_f32_e32 v22, v23, v22
	v_div_scale_f32 v23, vcc, 1.0, v20, 1.0
	v_mul_f32_e32 v85, v23, v22
	v_fma_f32 v86, -v21, v85, v23
	v_fmac_f32_e32 v85, v86, v22
	v_fma_f32 v21, -v21, v85, v23
	v_div_fmas_f32 v21, v21, v22, v85
	v_div_fixup_f32 v86, v21, v20, 1.0
	v_pk_mul_f32 v[20:21], v[34:35], v[86:87] op_sel_hi:[1,0]
	v_pk_mul_f32 v[22:23], v[36:37], v[86:87] op_sel_hi:[1,0]
	s_waitcnt vmcnt(0)
	v_pk_mul_f32 v[20:21], v[98:99], v[20:21]
	v_pk_mul_f32 v[22:23], v[100:101], v[22:23]
	v_cvt_pk_bf16_f32 v20, v20, v21
	v_cvt_pk_bf16_f32 v21, v22, v23
	global_store_dwordx2 v[44:45], v[20:21], off
	v_pk_mul_f32 v[34:35], v[46:47], v[86:87] op_sel_hi:[1,0]
	v_pk_mul_f32 v[30:31], v[30:31], v[86:87] op_sel_hi:[1,0]
	v_pk_mul_f32 v[32:33], v[32:33], v[86:87] op_sel_hi:[1,0]
	v_pk_mul_f32 v[28:29], v[28:29], v[86:87] op_sel_hi:[1,0]
	v_pk_mul_f32 v[24:25], v[24:25], v[86:87] op_sel_hi:[1,0]
	s_and_b64 vcc, exec, s[22:23]
	v_pk_mul_f32 v[20:21], v[224:225], v[34:35]
	v_pk_mul_f32 v[34:35], v[48:49], v[86:87] op_sel_hi:[1,0]
	v_cvt_pk_bf16_f32 v20, v20, v21
	v_pk_mul_f32 v[22:23], v[226:227], v[34:35]
	s_nop 0
	v_cvt_pk_bf16_f32 v21, v22, v23
	global_store_dwordx2 v[44:45], v[20:21], off offset:32
	v_pk_mul_f32 v[20:21], v[228:229], v[30:31]
	v_pk_mul_f32 v[22:23], v[230:231], v[32:33]
	v_cvt_pk_bf16_f32 v20, v20, v21
	v_cvt_pk_bf16_f32 v21, v22, v23
	global_store_dwordx2 v[44:45], v[20:21], off offset:64
	v_pk_mul_f32 v[30:31], v[94:95], v[86:87] op_sel_hi:[1,0]
	v_pk_mul_f32 v[22:23], v[234:235], v[28:29]
	v_pk_mul_f32 v[20:21], v[232:233], v[30:31]
	v_mov_b32_e32 v28, v26
	v_cvt_pk_bf16_f32 v20, v20, v21
	v_cvt_pk_bf16_f32 v21, v22, v23
	global_store_dwordx2 v[44:45], v[20:21], off offset:96
	v_mov_b32_e32 v29, v42
	v_mov_b32_e32 v42, v27
	v_pk_mul_f32 v[26:27], v[28:29], v[86:87] op_sel_hi:[1,0]
	v_pk_mul_f32 v[28:29], v[42:43], v[86:87] op_sel_hi:[1,0]
	v_pk_mul_f32 v[20:21], v[236:237], v[26:27]
	v_pk_mul_f32 v[22:23], v[238:239], v[28:29]
	v_cvt_pk_bf16_f32 v20, v20, v21
	v_cvt_pk_bf16_f32 v21, v22, v23
	global_store_dwordx2 v[44:45], v[20:21], off offset:128
	v_pk_mul_f32 v[26:27], v[38:39], v[86:87] op_sel_hi:[1,0]
	v_pk_mul_f32 v[28:29], v[40:41], v[86:87] op_sel_hi:[1,0]
	v_pk_mul_f32 v[20:21], v[240:241], v[26:27]
	v_pk_mul_f32 v[22:23], v[242:243], v[28:29]
	v_cvt_pk_bf16_f32 v20, v20, v21
	v_cvt_pk_bf16_f32 v21, v22, v23
	global_store_dwordx2 v[44:45], v[20:21], off offset:160
	v_pk_mul_f32 v[26:27], v[90:91], v[86:87] op_sel_hi:[1,0]
	v_pk_mul_f32 v[22:23], v[246:247], v[24:25]
	v_pk_mul_f32 v[20:21], v[244:245], v[26:27]
	v_pk_mul_f32 v[24:25], v[88:89], v[86:87] op_sel_hi:[1,0]
	v_cvt_pk_bf16_f32 v20, v20, v21
	v_cvt_pk_bf16_f32 v21, v22, v23
	global_store_dwordx2 v[44:45], v[20:21], off offset:192
	v_pk_mul_f32 v[22:23], v[130:131], v[86:87] op_sel_hi:[1,0]
	v_pk_mul_f32 v[20:21], v[250:251], v[24:25]
	v_pk_mul_f32 v[18:19], v[248:249], v[22:23]
	s_nop 0
	v_cvt_pk_bf16_f32 v18, v18, v19
	v_cvt_pk_bf16_f32 v19, v20, v21
	global_store_dwordx2 v[44:45], v[18:19], off offset:224
	s_cbranch_vccnz .LBB0_468
; __device__ __forceinline__ unsigned cvt_pk_bf16(float lo, float hi) { f32x2 v = {lo, hi}; bf16x2_t b = __builtin_convertvector(v, bf16x2_t); return __builtin_bit_cast(unsigned, b); }
; #define LAS __attribute__((address_space(3)))
; __device__ __forceinline__ void gmlp_phase(LAS unsigned char* lds, const bf16* Z, const float* w_s, const float* b_s, const float* gout, const float* ssv, const float* gv, bf16* Y, int vcu, int G, const int tid) {
;     ...
;         __syncthreads();
;         if (g != gcur) {
;             gcur = g;
; #pragma unroll
;             for (int i = 0; i < 8; ++i) { const int p = tid + 512 * i, t = p >> 5, s = (p & 31) * 4; const f32x4 w = *(const f32x4*)(w_s + (size_t)g * 16384 + t * 128 + s);
;                 u32x2 o; o.x = cvt_pk_bf16(s <= t ? w.x : 0.f, s + 1 <= t ? w.y : 0.f); o.y = cvt_pk_bf16(s + 2 <= t ? w.z : 0.f, s + 3 <= t ? w.w : 0.f);
;                 *(LAS u32x2*)(lds + t * WP + s * 2) = o; }
;         }
.LBB0_461:
	s_and_b32 s11, s10, 7
	s_cmp_eq_u32 s11, s9
	s_waitcnt vmcnt(8)
	s_barrier
	s_cbranch_scc1 .LBB0_463
	s_lshl_b32 s0, s11, 16
	v_lshl_add_u64 v[18:19], v[58:59], 0, s[0:1]
	v_lshl_add_u64 v[20:21], v[66:67], 2, v[18:19]
	global_load_dwordx4 v[20:23], v[20:21], off
	s_mov_b32 s9, s11
	s_waitcnt vmcnt(0)
	v_cndmask_b32_e64 v20, v20, 0, s[40:41]
	v_cndmask_b32_e64 v21, 0, v21, s[42:43]
	v_cvt_pk_bf16_f32 v20, v20, v21
	v_cndmask_b32_e64 v21, v22, 0, s[44:45]
	v_cndmask_b32_e64 v22, v23, 0, s[46:47]
	v_cvt_pk_bf16_f32 v21, v21, v22
	ds_write_b64 v111, v[20:21]
	v_lshl_add_u64 v[20:21], v[68:69], 2, v[18:19]
	global_load_dwordx4 v[20:23], v[20:21], off
	s_waitcnt vmcnt(0)
	v_cndmask_b32_e64 v20, v20, 0, s[48:49]
	v_cndmask_b32_e64 v21, 0, v21, s[50:51]
	v_cvt_pk_bf16_f32 v20, v20, v21
	v_cndmask_b32_e64 v21, v22, 0, s[52:53]
	v_cndmask_b32_e64 v22, v23, 0, s[54:55]
	v_cvt_pk_bf16_f32 v21, v21, v22
	ds_write_b64 v116, v[20:21]
	v_lshl_add_u64 v[20:21], v[70:71], 2, v[18:19]
	global_load_dwordx4 v[20:23], v[20:21], off
	s_waitcnt vmcnt(0)
	v_cndmask_b32_e64 v20, v20, 0, s[56:57]
	v_cndmask_b32_e64 v21, 0, v21, s[58:59]
	v_cvt_pk_bf16_f32 v20, v20, v21
	v_cndmask_b32_e64 v21, v22, 0, s[60:61]
	v_cndmask_b32_e64 v22, v23, 0, s[62:63]
	v_cvt_pk_bf16_f32 v21, v21, v22
	ds_write_b64 v117, v[20:21]
	v_lshl_add_u64 v[20:21], v[72:73], 2, v[18:19]
	global_load_dwordx4 v[20:23], v[20:21], off
	s_waitcnt vmcnt(0)
	v_cndmask_b32_e64 v20, v20, 0, s[64:65]
	v_cndmask_b32_e64 v21, 0, v21, s[66:67]
	v_cvt_pk_bf16_f32 v20, v20, v21
	v_cndmask_b32_e64 v21, v22, 0, s[68:69]
	v_cndmask_b32_e64 v22, v23, 0, s[70:71]
	v_cvt_pk_bf16_f32 v21, v21, v22
	ds_write_b64 v118, v[20:21]
	v_lshl_add_u64 v[20:21], v[74:75], 2, v[18:19]
	global_load_dwordx4 v[20:23], v[20:21], off
	s_waitcnt vmcnt(0)
	v_cndmask_b32_e64 v20, v20, 0, s[72:73]
	v_cndmask_b32_e64 v21, 0, v21, s[74:75]
	v_cvt_pk_bf16_f32 v20, v20, v21
	v_cndmask_b32_e64 v21, v22, 0, s[76:77]
	v_cndmask_b32_e64 v22, v23, 0, s[78:79]
	v_cvt_pk_bf16_f32 v21, v21, v22
	ds_write_b64 v119, v[20:21]
	v_lshl_add_u64 v[20:21], v[76:77], 2, v[18:19]
	global_load_dwordx4 v[20:23], v[20:21], off
	s_waitcnt vmcnt(0)
	v_cndmask_b32_e64 v20, v20, 0, s[80:81]
	v_cndmask_b32_e64 v21, 0, v21, s[82:83]
	v_cvt_pk_bf16_f32 v20, v20, v21
	v_cndmask_b32_e64 v21, v22, 0, s[84:85]
	v_cndmask_b32_e64 v22, v23, 0, s[86:87]
	v_cvt_pk_bf16_f32 v21, v21, v22
	ds_write_b64 v120, v[20:21]
	v_lshl_add_u64 v[20:21], v[78:79], 2, v[18:19]
	global_load_dwordx4 v[20:23], v[20:21], off
	v_lshl_add_u64 v[18:19], v[80:81], 2, v[18:19]
	s_waitcnt vmcnt(0)
	v_cndmask_b32_e64 v20, v20, 0, s[88:89]
	v_cndmask_b32_e64 v21, 0, v21, s[90:91]
	v_cvt_pk_bf16_f32 v20, v20, v21
	v_cndmask_b32_e64 v21, v22, 0, s[92:93]
	v_cndmask_b32_e64 v22, v23, 0, s[94:95]
	v_cvt_pk_bf16_f32 v21, v21, v22
	ds_write_b64 v121, v[20:21]
	global_load_dwordx4 v[18:21], v[18:19], off
	s_waitcnt vmcnt(0)
	v_cndmask_b32_e64 v18, v18, 0, s[96:97]
	v_cndmask_b32_e64 v19, 0, v19, s[98:99]
	v_cvt_pk_bf16_f32 v18, v18, v19
	v_cndmask_b32_e64 v19, v20, 0, s[4:5]
	v_cndmask_b32_e64 v20, v21, 0, s[6:7]
	v_cvt_pk_bf16_f32 v19, v19, v20
	ds_write_b64 v122, v[18:19]

; #define LAS __attribute__((address_space(3)))
; __device__ __forceinline__ void gmlp_phase(LAS unsigned char* lds, const bf16* Z, const float* w_s, const float* b_s, const float* gout, const float* ssv, const float* gv, bf16* Y, int vcu, int G, const int tid) {
;     ...
;         const int nsb = (wid >> 1) + 1;
;         for (int sb = 0; sb < nsb; ++sb) {
;             const bf16x8 wf = *(const LAS bf16x8*)(lds + (16 * wid + l16) * WP + sb * 64 + q4 * 16);
; #pragma unroll
;             for (int d = 0; d < 8; ++d) { const bf16x8 vf = *(const LAS bf16x8*)(lds + WBYTES + (16 * d + l16) * WP + sb * 64 + q4 * 16); acc[d] = __builtin_amdgcn_mfma_f32_16x16x32_bf16(vf, wf, acc[d], 0, 0, 0); }
;         }
.LBB0_467:
	ds_read_b128 v[128:131], v85
	ds_read_b128 v[132:135], v127
	ds_read_b128 v[154:157], v127 offset:4368
	ds_read_b128 v[158:161], v127 offset:8736
	ds_read_b128 v[162:165], v127 offset:13104
	ds_read_b128 v[166:169], v127 offset:17472
	ds_read_b128 v[170:173], v127 offset:21840
	ds_read_b128 v[178:181], v127 offset:26208
	ds_read_b128 v[182:185], v127 offset:30576
	s_add_i32 s10, s10, -1
	v_add_u32_e32 v85, 64, v85
	v_add_u32_e32 v127, 64, v127
	s_cmp_eq_u32 s10, 0
	s_waitcnt lgkmcnt(7)
	v_mfma_f32_16x16x32_bf16 v[34:37], v[132:135], v[128:131], v[34:37]
	s_waitcnt lgkmcnt(6)
	v_mfma_f32_16x16x32_bf16 v[46:49], v[154:157], v[128:131], v[46:49]
	s_waitcnt lgkmcnt(5)
	v_mfma_f32_16x16x32_bf16 v[30:33], v[158:161], v[128:131], v[30:33]
	s_waitcnt lgkmcnt(4)
	v_mfma_f32_16x16x32_bf16 v[26:29], v[162:165], v[128:131], v[26:29]
	s_waitcnt lgkmcnt(3)
	v_mfma_f32_16x16x32_bf16 v[42:45], v[166:169], v[128:131], v[42:45]
	s_waitcnt lgkmcnt(2)
	v_mfma_f32_16x16x32_bf16 v[38:41], v[170:173], v[128:131], v[38:41]
	s_waitcnt lgkmcnt(1)
	v_mfma_f32_16x16x32_bf16 v[22:25], v[178:181], v[128:131], v[22:25]
	s_waitcnt lgkmcnt(0)
	v_mfma_f32_16x16x32_bf16 v[18:21], v[182:185], v[128:131], v[18:21]
	s_cbranch_scc0 .LBB0_467
	s_branch .LBB0_460
